# gdn_passB: 12 more bf16 packs (sdwa bit-trick form) -> v_cvt_pk_bf16_f32
# baseline (speedup 1.0000x reference)
.LBB0_726:
	v_cvt_pk_bf16_f32 v64, v32, v33
	v_cvt_pk_bf16_f32 v65, v34, v35
	v_cvt_pk_bf16_f32 v66, v56, v57
	v_cvt_pk_bf16_f32 v67, v58, v59
	v_cvt_pk_bf16_f32 v68, v60, v61
	v_cvt_pk_bf16_f32 v69, v62, v63
	v_cvt_pk_bf16_f32 v70, v36, v37
	v_cvt_pk_bf16_f32 v71, v38, v39
	v_cvt_pk_bf16_f32 v72, v40, v41
	v_cvt_pk_bf16_f32 v73, v42, v43
	v_cvt_pk_bf16_f32 v74, v48, v49
	v_cvt_pk_bf16_f32 v75, v50, v51
	v_cvt_pk_bf16_f32 v80, v52, v53
	v_cvt_pk_bf16_f32 v81, v54, v55
	v_cvt_pk_bf16_f32 v82, v44, v45
	v_add_u32_e32 v184, 0x8800, v172
	v_cvt_pk_bf16_f32 v83, v46, v47
	ds_write2_b64 v158, v[64:65], v[66:67] offset1:4
	ds_read2_b64 v[76:79], v184 offset0:128 offset1:132
	ds_write2_b64 v158, v[68:69], v[70:71] offset0:8 offset1:12
	ds_write2_b64 v158, v[72:73], v[74:75] offset0:16 offset1:20
	ds_write2_b64 v158, v[80:81], v[82:83] offset0:24 offset1:28
	v_add_u32_e32 v185, 0x8800, v164
	v_add_u32_e32 v186, 0x9800, v164
	v_add_u32_e32 v187, 0xa800, v164
	ds_read2_b64 v[84:87], v185 offset0:128 offset1:132
	ds_read2_b64 v[172:175], v186 offset0:160 offset1:164
	ds_read2_b64 v[176:179], v187 offset0:192 offset1:196
	s_waitcnt lgkmcnt(6)
	v_mfma_f32_16x16x32_bf16 v[76:79], v[76:79], v[64:67], 0
	ds_read2_b64 v[180:183], v184 offset0:136 offset1:140
	v_lshl_add_u64 v[100:101], v[100:101], 0, s[6:7]
	v_lshl_add_u64 v[102:103], v[102:103], 0, s[6:7]
	s_waitcnt lgkmcnt(3)
	v_mfma_f32_16x16x32_bf16 v[84:87], v[84:87], v[64:67], 0
	v_lshl_add_u64 v[104:105], v[104:105], 0, s[6:7]
	v_lshl_add_u64 v[106:107], v[106:107], 0, s[6:7]
	v_lshl_add_u64 v[108:109], v[108:109], 0, s[6:7]
	s_waitcnt lgkmcnt(2)
	v_mfma_f32_16x16x32_bf16 v[172:175], v[172:175], v[64:67], 0
	v_lshl_add_u64 v[110:111], v[110:111], 0, s[6:7]
	v_lshl_add_u64 v[112:113], v[112:113], 0, s[6:7]
	v_lshl_add_u64 v[114:115], v[114:115], 0, s[6:7]
	s_waitcnt lgkmcnt(1)
	v_mfma_f32_16x16x32_bf16 v[64:67], v[176:179], v[64:67], 0
	ds_read2_b64 v[176:179], v185 offset0:136 offset1:140
	v_lshl_add_u64 v[116:117], v[116:117], 0, s[6:7]
	s_cmp_lt_u32 s11, 30
	s_waitcnt lgkmcnt(1)
	v_mfma_f32_16x16x32_bf16 v[76:79], v[180:183], v[68:71], v[76:79]
	ds_read2_b64 v[180:183], v186 offset0:168 offset1:172
	s_mov_b32 s14, s11
	s_waitcnt lgkmcnt(1)
	v_mfma_f32_16x16x32_bf16 v[84:87], v[176:179], v[68:71], v[84:87]
	ds_read2_b64 v[176:179], v187 offset0:200 offset1:204
	s_waitcnt lgkmcnt(1)
	v_mfma_f32_16x16x32_bf16 v[172:175], v[180:183], v[68:71], v[172:175]
	ds_read2_b64 v[180:183], v184 offset0:144 offset1:148
	s_waitcnt lgkmcnt(1)
	v_mfma_f32_16x16x32_bf16 v[64:67], v[176:179], v[68:71], v[64:67]
	ds_read2_b64 v[68:71], v185 offset0:144 offset1:148
	ds_read2_b64 v[176:179], v186 offset0:176 offset1:180
	s_waitcnt lgkmcnt(1)
	v_mfma_f32_16x16x32_bf16 v[68:71], v[68:71], v[72:75], v[84:87]
	s_nop 2
	ds_read2_b64 v[84:87], v187 offset0:208 offset1:212
	s_waitcnt lgkmcnt(1)
	v_mfma_f32_16x16x32_bf16 v[172:175], v[176:179], v[72:75], v[172:175]
	ds_read2_b64 v[176:179], v184 offset0:152 offset1:156
	v_mfma_f32_16x16x32_bf16 v[76:79], v[180:183], v[72:75], v[76:79]
	s_waitcnt lgkmcnt(1)
	v_mfma_f32_16x16x32_bf16 v[84:87], v[84:87], v[72:75], v[64:67]
	ds_read2_b64 v[72:75], v186 offset0:184 offset1:188
	s_nop 1
	ds_read2_b64 v[64:67], v185 offset0:152 offset1:156
	ds_read2_b64 v[184:187], v187 offset0:216 offset1:220
	s_waitcnt lgkmcnt(3)
	v_mfma_f32_16x16x32_bf16 v[176:179], v[176:179], v[80:83], v[76:79]
	s_waitcnt lgkmcnt(1)
	v_mfma_f32_16x16x32_bf16 v[180:183], v[64:67], v[80:83], v[68:71]
	v_mfma_f32_16x16x32_bf16 v[172:175], v[72:75], v[80:83], v[172:175]
	ds_read_b128 v[76:79], v162
	ds_read_b128 v[64:67], v162 offset:2176
	ds_read_b128 v[72:75], v163
	ds_read_b128 v[68:71], v162 offset:3264
	s_waitcnt lgkmcnt(4)
	v_mfma_f32_16x16x32_bf16 v[184:187], v[184:187], v[80:83], v[84:87]
	v_lshlrev_b32_e32 v81, 16, v139
	v_lshlrev_b32_e32 v80, 16, v138
	v_mov_b32_e32 v82, v176
	v_mov_b32_e32 v83, v178
	v_pk_add_f32 v[80:81], v[80:81], v[82:83] neg_lo:[0,1] neg_hi:[0,1]
	v_and_b32_e32 v83, 0xffff0000, v139
	v_and_b32_e32 v82, 0xffff0000, v138
	v_mov_b32_e32 v178, v177
	v_pk_add_f32 v[82:83], v[82:83], v[178:179] neg_lo:[0,1] neg_hi:[0,1]
	v_cvt_pk_bf16_f32 v85, v81, v83
	v_cvt_pk_bf16_f32 v84, v80, v82
	v_lshlrev_b32_e32 v81, 16, v135
	v_lshlrev_b32_e32 v80, 16, v134
	v_mov_b32_e32 v82, v180
	v_mov_b32_e32 v83, v182
	v_pk_add_f32 v[80:81], v[80:81], v[82:83] neg_lo:[0,1] neg_hi:[0,1]
	v_and_b32_e32 v83, 0xffff0000, v135
	v_and_b32_e32 v82, 0xffff0000, v134
	v_mov_b32_e32 v182, v181
	v_pk_add_f32 v[82:83], v[82:83], v[182:183] neg_lo:[0,1] neg_hi:[0,1]
	v_cvt_pk_bf16_f32 v87, v81, v83
	v_cvt_pk_bf16_f32 v86, v80, v82
	v_lshlrev_b32_e32 v81, 16, v133
	v_lshlrev_b32_e32 v80, 16, v132
	v_mov_b32_e32 v82, v172
	v_mov_b32_e32 v83, v174
	v_pk_add_f32 v[80:81], v[80:81], v[82:83] neg_lo:[0,1] neg_hi:[0,1]
	v_and_b32_e32 v83, 0xffff0000, v133
	v_and_b32_e32 v82, 0xffff0000, v132
	v_mov_b32_e32 v174, v173
	v_pk_add_f32 v[82:83], v[82:83], v[174:175] neg_lo:[0,1] neg_hi:[0,1]
	v_cvt_pk_bf16_f32 v81, v81, v83
	v_cvt_pk_bf16_f32 v80, v80, v82
	v_lshlrev_b32_e32 v83, 16, v129
	v_lshlrev_b32_e32 v82, 16, v128
	v_mov_b32_e32 v132, v184
	v_mov_b32_e32 v133, v186
	v_pk_add_f32 v[82:83], v[82:83], v[132:133] neg_lo:[0,1] neg_hi:[0,1]
	v_and_b32_e32 v129, 0xffff0000, v129
	v_and_b32_e32 v128, 0xffff0000, v128
	v_mov_b32_e32 v186, v185
	v_pk_add_f32 v[128:129], v[128:129], v[186:187] neg_lo:[0,1] neg_hi:[0,1]
	v_and_b32_sdwa v132, v83, v165 dst_sel:DWORD dst_unused:UNUSED_PAD src0_sel:WORD_1 src1_sel:DWORD
	v_and_b32_sdwa v133, v82, v165 dst_sel:DWORD dst_unused:UNUSED_PAD src0_sel:WORD_1 src1_sel:DWORD
	v_add3_u32 v82, v82, v133, s2
	v_add3_u32 v83, v83, v132, s2
	v_and_b32_sdwa v132, v129, v165 dst_sel:DWORD dst_unused:UNUSED_PAD src0_sel:WORD_1 src1_sel:DWORD
	v_and_b32_sdwa v133, v128, v165 dst_sel:DWORD dst_unused:UNUSED_PAD src0_sel:WORD_1 src1_sel:DWORD
	v_add_u32_e32 v139, 0xd000, v171
	v_add3_u32 v129, v129, v132, s2
	v_add3_u32 v138, v128, v133, s2
	ds_read2_b64 v[132:135], v139 offset1:4
	ds_bpermute_b32 v128, v159, v89
	v_and_b32_e32 v129, 0xffff0000, v129
	v_and_b32_e32 v138, 0xffff0000, v138
	v_or_b32_sdwa v83, v129, v83 dst_sel:DWORD dst_unused:UNUSED_PAD src0_sel:DWORD src1_sel:WORD_1
	v_or_b32_sdwa v82, v138, v82 dst_sel:DWORD dst_unused:UNUSED_PAD src0_sel:DWORD src1_sel:WORD_1
	ds_write2_b64 v170, v[84:85], v[86:87] offset0:32 offset1:36
	ds_write2_b64 v170, v[80:81], v[82:83] offset0:40 offset1:44
	s_waitcnt lgkmcnt(2)
	v_pk_mul_f32 v[34:35], v[34:35], v[128:129] op_sel_hi:[1,0]
	v_pk_mul_f32 v[32:33], v[32:33], v[128:129] op_sel_hi:[1,0]
	v_add_u32_e32 v129, 0xd000, v169
	v_pk_mul_f32 v[58:59], v[58:59], v[128:129] op_sel_hi:[1,0]
	v_mfma_f32_16x16x32_bf16 v[32:35], v[132:135], v[84:87], v[32:35]
	ds_read2_b64 v[132:135], v129 offset1:4
	v_pk_mul_f32 v[56:57], v[56:57], v[128:129] op_sel_hi:[1,0]
	v_add_u32_e32 v138, 0xd800, v169
	v_pk_mul_f32 v[62:63], v[62:63], v[128:129] op_sel_hi:[1,0]
	s_waitcnt lgkmcnt(0)
	v_mfma_f32_16x16x32_bf16 v[56:59], v[132:135], v[84:87], v[56:59]
	ds_read2_b64 v[132:135], v138 offset0:32 offset1:36
	v_pk_mul_f32 v[60:61], v[60:61], v[128:129] op_sel_hi:[1,0]
	v_add_u32_e32 v178, 0xe000, v169
	v_pk_mul_f32 v[38:39], v[38:39], v[128:129] op_sel_hi:[1,0]
	s_waitcnt lgkmcnt(0)
	v_mfma_f32_16x16x32_bf16 v[132:135], v[132:135], v[84:87], v[60:63]
	s_nop 2
	ds_read2_b64 v[60:63], v178 offset0:64 offset1:68
	v_pk_mul_f32 v[36:37], v[36:37], v[128:129] op_sel_hi:[1,0]
	v_add_u32_e32 v179, 0xf000, v171
	v_pk_mul_f32 v[42:43], v[42:43], v[128:129] op_sel_hi:[1,0]
	s_waitcnt lgkmcnt(0)
	v_mfma_f32_16x16x32_bf16 v[36:39], v[60:63], v[84:87], v[36:39]
	ds_read2_b64 v[60:63], v179 offset0:128 offset1:132
	v_pk_mul_f32 v[40:41], v[40:41], v[128:129] op_sel_hi:[1,0]
	v_add_u32_e32 v180, 0xf800, v171
	v_pk_mul_f32 v[50:51], v[50:51], v[128:129] op_sel_hi:[1,0]
	s_waitcnt lgkmcnt(0)
	v_mfma_f32_16x16x32_bf16 v[40:43], v[60:63], v[84:87], v[40:43]
	ds_read2_b64 v[60:63], v180 offset0:160 offset1:164
	v_pk_mul_f32 v[48:49], v[48:49], v[128:129] op_sel_hi:[1,0]
	v_pk_mul_f32 v[54:55], v[54:55], v[128:129] op_sel_hi:[1,0]
	v_pk_mul_f32 v[52:53], v[52:53], v[128:129] op_sel_hi:[1,0]
	s_waitcnt lgkmcnt(0)
	v_mfma_f32_16x16x32_bf16 v[170:173], v[60:63], v[84:87], v[48:51]
	s_nop 2
	v_add_u32_e32 v48, 0x3000, v160
	ds_read2_b64 v[48:51], v48 offset0:192 offset1:196
	v_pk_mul_f32 v[46:47], v[46:47], v[128:129] op_sel_hi:[1,0]
	s_waitcnt lgkmcnt(0)
	v_mfma_f32_16x16x32_bf16 v[174:177], v[48:51], v[84:87], v[52:55]
	v_add_u32_e32 v48, 0x3800, v160
	ds_read2_b64 v[48:51], v48 offset0:224 offset1:228
	v_pk_mul_f32 v[44:45], v[44:45], v[128:129] op_sel_hi:[1,0]
	v_add_co_u32_e32 v128, vcc, s9, v148
	s_waitcnt lgkmcnt(0)
	v_mfma_f32_16x16x32_bf16 v[84:87], v[48:51], v[84:87], v[44:47]
	s_nop 2
	ds_read2_b64 v[44:47], v139 offset0:8 offset1:12
	v_add_u32_e32 v159, 8, v159
	s_waitcnt lgkmcnt(0)
	v_mfma_f32_16x16x32_bf16 v[32:35], v[44:47], v[80:83], v[32:35]
	ds_read2_b64 v[44:47], v129 offset0:8 offset1:12
	ds_read2_b64 v[48:51], v138 offset0:40 offset1:44
	v_addc_co_u32_e32 v129, vcc, 0, v149, vcc
	s_waitcnt lgkmcnt(1)
	v_mfma_f32_16x16x32_bf16 v[60:63], v[44:47], v[80:83], v[56:59]
	ds_read2_b64 v[44:47], v178 offset0:72 offset1:76
	v_add_co_u32_e32 v52, vcc, s9, v144
	s_waitcnt lgkmcnt(1)
	v_mfma_f32_16x16x32_bf16 v[56:59], v[48:51], v[80:83], v[132:135]
	ds_read2_b64 v[48:51], v179 offset0:136 offset1:140
	v_addc_co_u32_e32 v53, vcc, 0, v145, vcc
	global_store_dwordx4 v[128:129], v[76:79], off
	global_store_dwordx4 v[52:53], v[72:75], off
	global_store_dwordx4 v[128:129], v[64:67], off offset:2048
	global_store_dwordx4 v[128:129], v[68:71], off offset:3072
	s_waitcnt lgkmcnt(1)
	v_mfma_f32_16x16x32_bf16 v[52:55], v[44:47], v[80:83], v[36:39]
	s_nop 2
	ds_read2_b64 v[36:39], v180 offset0:168 offset1:172
	ds_read_b128 v[64:67], v167 offset:4352
	v_add_co_u32_e32 v72, vcc, s10, v142
	s_waitcnt lgkmcnt(2)
	v_mfma_f32_16x16x32_bf16 v[48:51], v[48:51], v[80:83], v[40:43]
	v_addc_co_u32_e32 v73, vcc, 0, v143, vcc
	s_waitcnt vmcnt(13)
	v_mov_b64_e32 v[138:139], v[118:119]
	v_add_u32_e32 v40, 0x3000, v161
	ds_read2_b64 v[40:43], v40 offset0:192 offset1:196
	s_waitcnt lgkmcnt(2)
	v_mfma_f32_16x16x32_bf16 v[44:47], v[36:39], v[80:83], v[170:173]
	v_add_u32_e32 v36, 0x3800, v161
	ds_read2_b64 v[36:39], v36 offset0:224 offset1:228
	ds_read_b128 v[68:71], v168 offset:4352
	s_waitcnt lgkmcnt(3)
	global_store_dwordx4 v[72:73], v[64:67], off
	s_waitcnt lgkmcnt(2)
	v_mfma_f32_16x16x32_bf16 v[40:43], v[40:43], v[80:83], v[174:177]
	v_add_co_u32_e32 v64, vcc, s10, v146
	s_waitcnt vmcnt(13)
	v_mov_b64_e32 v[134:135], v[120:121]
	v_addc_co_u32_e32 v65, vcc, 0, v147, vcc
	s_waitcnt lgkmcnt(0)
	global_store_dwordx4 v[64:65], v[68:71], off
	v_mfma_f32_16x16x32_bf16 v[36:39], v[36:39], v[80:83], v[84:87]
	s_waitcnt lgkmcnt(0)
	s_barrier
	s_waitcnt vmcnt(13)
	v_mov_b64_e32 v[132:133], v[122:123]
	s_waitcnt vmcnt(12)
	v_mov_b64_e32 v[128:129], v[124:125]
	s_cbranch_scc0 .LBB0_733

.LBB0_729:
	v_cvt_pk_bf16_f32 v64, v32, v33
	v_cvt_pk_bf16_f32 v65, v34, v35
	v_cvt_pk_bf16_f32 v66, v60, v61
	v_cvt_pk_bf16_f32 v67, v62, v63
	v_cvt_pk_bf16_f32 v68, v56, v57
	v_cvt_pk_bf16_f32 v69, v58, v59
	v_cvt_pk_bf16_f32 v70, v52, v53
	v_cvt_pk_bf16_f32 v71, v54, v55
	v_cvt_pk_bf16_f32 v72, v48, v49
	v_cvt_pk_bf16_f32 v73, v50, v51
	v_cvt_pk_bf16_f32 v74, v44, v45
	v_cvt_pk_bf16_f32 v75, v46, v47
	v_cvt_pk_bf16_f32 v80, v40, v41
	v_cvt_pk_bf16_f32 v81, v42, v43
	v_cvt_pk_bf16_f32 v82, v36, v37
	v_add_u32_e32 v172, v155, v154
	v_cvt_pk_bf16_f32 v83, v38, v39
	ds_read2_b64 v[76:79], v172 offset1:4
	ds_write2_b64 v158, v[64:65], v[66:67] offset1:4
	ds_write2_b64 v158, v[68:69], v[70:71] offset0:8 offset1:12
	ds_write2_b64 v158, v[72:73], v[74:75] offset0:16 offset1:20
	ds_write2_b64 v158, v[80:81], v[82:83] offset0:24 offset1:28
	v_add_u32_e32 v170, 0x1000, v164
	v_add_u32_e32 v171, 0x2000, v164
	ds_read2_b64 v[84:87], v164 offset1:4
	ds_read2_b64 v[142:145], v170 offset0:32 offset1:36
	ds_read2_b64 v[146:149], v171 offset0:64 offset1:68
	s_waitcnt lgkmcnt(7)
	v_mfma_f32_16x16x32_bf16 v[76:79], v[76:79], v[64:67], 0
	ds_read2_b64 v[174:177], v172 offset0:8 offset1:12
	ds_read2_b64 v[178:181], v171 offset0:88 offset1:92
	v_add_u32_e32 v173, -4, v159
	s_waitcnt lgkmcnt(4)
	v_mfma_f32_16x16x32_bf16 v[84:87], v[84:87], v[64:67], 0
	s_add_i32 s14, s14, 3
	s_cmp_gt_u32 s14, 30
	s_waitcnt lgkmcnt(3)
	v_mfma_f32_16x16x32_bf16 v[142:145], v[142:145], v[64:67], 0
	s_waitcnt lgkmcnt(2)
	v_mfma_f32_16x16x32_bf16 v[64:67], v[146:149], v[64:67], 0
	ds_read2_b64 v[146:149], v164 offset0:8 offset1:12
	s_waitcnt lgkmcnt(2)
	v_mfma_f32_16x16x32_bf16 v[76:79], v[174:177], v[68:71], v[76:79]
	ds_read2_b64 v[174:177], v170 offset0:40 offset1:44
	s_waitcnt lgkmcnt(1)
	v_mfma_f32_16x16x32_bf16 v[84:87], v[146:149], v[68:71], v[84:87]
	ds_read2_b64 v[146:149], v171 offset0:72 offset1:76
	s_waitcnt lgkmcnt(1)
	v_mfma_f32_16x16x32_bf16 v[142:145], v[174:177], v[68:71], v[142:145]
	ds_read2_b64 v[174:177], v172 offset0:16 offset1:20
	s_waitcnt lgkmcnt(1)
	v_mfma_f32_16x16x32_bf16 v[64:67], v[146:149], v[68:71], v[64:67]
	ds_read2_b64 v[68:71], v164 offset0:16 offset1:20
	ds_read2_b64 v[146:149], v170 offset0:48 offset1:52
	s_waitcnt lgkmcnt(1)
	v_mfma_f32_16x16x32_bf16 v[68:71], v[68:71], v[72:75], v[84:87]
	s_nop 2
	ds_read2_b64 v[84:87], v171 offset0:80 offset1:84
	v_add_u32_e32 v171, v155, v157
	v_add_u32_e32 v182, 0x7800, v171
	s_waitcnt lgkmcnt(1)
	v_mfma_f32_16x16x32_bf16 v[142:145], v[146:149], v[72:75], v[142:145]
	ds_read2_b64 v[146:149], v172 offset0:24 offset1:28
	v_add_u32_e32 v183, 0x8000, v171
	v_mfma_f32_16x16x32_bf16 v[76:79], v[174:177], v[72:75], v[76:79]
	s_waitcnt lgkmcnt(1)
	v_mfma_f32_16x16x32_bf16 v[84:87], v[84:87], v[72:75], v[64:67]
	ds_read2_b64 v[72:75], v170 offset0:56 offset1:60
	v_add_u32_e32 v170, 0x1000, v166
	s_nop 0
	ds_read2_b64 v[64:67], v164 offset0:24 offset1:28
	s_waitcnt lgkmcnt(2)
	v_mfma_f32_16x16x32_bf16 v[146:149], v[146:149], v[80:83], v[76:79]
	s_waitcnt lgkmcnt(0)
	v_mfma_f32_16x16x32_bf16 v[174:177], v[64:67], v[80:83], v[68:71]
	v_mfma_f32_16x16x32_bf16 v[142:145], v[72:75], v[80:83], v[142:145]
	ds_read_b128 v[76:79], v162
	ds_read_b128 v[64:67], v162 offset:2176
	ds_read_b128 v[72:75], v163
	ds_read_b128 v[68:71], v162 offset:3264
	v_mfma_f32_16x16x32_bf16 v[178:181], v[178:181], v[80:83], v[84:87]
	v_lshlrev_b32_e32 v81, 16, v141
	v_lshlrev_b32_e32 v80, 16, v140
	v_mov_b32_e32 v82, v146
	v_mov_b32_e32 v83, v148
	v_pk_add_f32 v[80:81], v[80:81], v[82:83] neg_lo:[0,1] neg_hi:[0,1]
	v_and_b32_e32 v83, 0xffff0000, v141
	v_and_b32_e32 v82, 0xffff0000, v140
	v_mov_b32_e32 v148, v147
	v_pk_add_f32 v[82:83], v[82:83], v[148:149] neg_lo:[0,1] neg_hi:[0,1]
	v_cvt_pk_bf16_f32 v85, v81, v83
	v_cvt_pk_bf16_f32 v84, v80, v82
	v_lshlrev_b32_e32 v81, 16, v137
	v_lshlrev_b32_e32 v80, 16, v136
	v_mov_b32_e32 v82, v174
	v_mov_b32_e32 v83, v176
	v_pk_add_f32 v[80:81], v[80:81], v[82:83] neg_lo:[0,1] neg_hi:[0,1]
	v_and_b32_e32 v83, 0xffff0000, v137
	v_and_b32_e32 v82, 0xffff0000, v136
	v_mov_b32_e32 v176, v175
	v_pk_add_f32 v[82:83], v[82:83], v[176:177] neg_lo:[0,1] neg_hi:[0,1]
	v_cvt_pk_bf16_f32 v87, v81, v83
	v_cvt_pk_bf16_f32 v86, v80, v82
	v_lshlrev_b32_e32 v81, 16, v131
	v_lshlrev_b32_e32 v80, 16, v130
	v_mov_b32_e32 v82, v142
	v_mov_b32_e32 v83, v144
	v_pk_add_f32 v[80:81], v[80:81], v[82:83] neg_lo:[0,1] neg_hi:[0,1]
	v_and_b32_e32 v83, 0xffff0000, v131
	v_and_b32_e32 v82, 0xffff0000, v130
	v_mov_b32_e32 v144, v143
	v_pk_add_f32 v[82:83], v[82:83], v[144:145] neg_lo:[0,1] neg_hi:[0,1]
	v_cvt_pk_bf16_f32 v81, v81, v83
	v_cvt_pk_bf16_f32 v80, v80, v82
	v_lshlrev_b32_e32 v83, 16, v127
	v_lshlrev_b32_e32 v82, 16, v126
	v_mov_b32_e32 v130, v178
	v_mov_b32_e32 v131, v180
	v_pk_add_f32 v[82:83], v[82:83], v[130:131] neg_lo:[0,1] neg_hi:[0,1]
	v_and_b32_e32 v127, 0xffff0000, v127
	v_and_b32_e32 v126, 0xffff0000, v126
	v_mov_b32_e32 v180, v179
	v_pk_add_f32 v[126:127], v[126:127], v[180:181] neg_lo:[0,1] neg_hi:[0,1]
	v_and_b32_sdwa v131, v82, v165 dst_sel:DWORD dst_unused:UNUSED_PAD src0_sel:WORD_1 src1_sel:DWORD
	v_and_b32_sdwa v130, v83, v165 dst_sel:DWORD dst_unused:UNUSED_PAD src0_sel:WORD_1 src1_sel:DWORD
	v_add3_u32 v82, v82, v131, s2
	v_and_b32_sdwa v131, v126, v165 dst_sel:DWORD dst_unused:UNUSED_PAD src0_sel:WORD_1 src1_sel:DWORD
	v_add3_u32 v83, v83, v130, s2
	v_and_b32_sdwa v130, v127, v165 dst_sel:DWORD dst_unused:UNUSED_PAD src0_sel:WORD_1 src1_sel:DWORD
	v_add3_u32 v126, v126, v131, s2
	v_add_u32_e32 v131, 0x4000, v171
	v_add3_u32 v127, v127, v130, s2
	ds_read2_b64 v[140:143], v131 offset0:128 offset1:132
	v_and_b32_e32 v127, 0xffff0000, v127
	v_and_b32_e32 v130, 0xffff0000, v126
	v_or_b32_sdwa v83, v127, v83 dst_sel:DWORD dst_unused:UNUSED_PAD src0_sel:DWORD src1_sel:WORD_1
	v_or_b32_sdwa v82, v130, v82 dst_sel:DWORD dst_unused:UNUSED_PAD src0_sel:DWORD src1_sel:WORD_1
	ds_write2_b64 v170, v[84:85], v[86:87] offset0:32 offset1:36
	ds_bpermute_b32 v126, v173, v89
	ds_write2_b64 v170, v[80:81], v[82:83] offset0:40 offset1:44
	v_add_u32_e32 v127, 0x4000, v169
	ds_read2_b64 v[144:147], v127 offset0:128 offset1:132
	v_add_u32_e32 v130, 0x4800, v169
	s_waitcnt lgkmcnt(2)
	v_pk_mul_f32 v[34:35], v[34:35], v[126:127] op_sel_hi:[1,0]
	v_pk_mul_f32 v[32:33], v[32:33], v[126:127] op_sel_hi:[1,0]
	v_pk_mul_f32 v[62:63], v[62:63], v[126:127] op_sel_hi:[1,0]
	v_pk_mul_f32 v[60:61], v[60:61], v[126:127] op_sel_hi:[1,0]
	v_mfma_f32_16x16x32_bf16 v[32:35], v[140:143], v[84:87], v[32:35]
	ds_read2_b64 v[140:143], v130 offset0:160 offset1:164
	v_add_u32_e32 v136, 0x5000, v169
	v_pk_mul_f32 v[58:59], v[58:59], v[126:127] op_sel_hi:[1,0]
	s_waitcnt lgkmcnt(1)
	v_mfma_f32_16x16x32_bf16 v[60:63], v[144:147], v[84:87], v[60:63]
	ds_read2_b64 v[144:147], v136 offset0:192 offset1:196
	v_pk_mul_f32 v[56:57], v[56:57], v[126:127] op_sel_hi:[1,0]
	v_add_u32_e32 v137, 0x6800, v171
	v_pk_mul_f32 v[54:55], v[54:55], v[126:127] op_sel_hi:[1,0]
	s_waitcnt lgkmcnt(1)
	v_mfma_f32_16x16x32_bf16 v[140:143], v[140:143], v[84:87], v[56:59]
	v_mul_f32_e64 v52, v52, v126
	v_mul_f32_e64 v53, v53, v126
	v_add_u32_e32 v173, 0x7000, v171
	ds_read2_b64 v[56:59], v137 offset1:4
	s_waitcnt lgkmcnt(1)
	v_mfma_f32_16x16x32_bf16 v[52:55], v[144:147], v[84:87], v[52:55]
	ds_read2_b64 v[144:147], v173 offset0:32 offset1:36
	v_pk_mul_f32 v[50:51], v[50:51], v[126:127] op_sel_hi:[1,0]
	v_pk_mul_f32 v[48:49], v[48:49], v[126:127] op_sel_hi:[1,0]
	v_pk_mul_f32 v[46:47], v[46:47], v[126:127] op_sel_hi:[1,0]
	v_pk_mul_f32 v[44:45], v[44:45], v[126:127] op_sel_hi:[1,0]
	s_waitcnt lgkmcnt(1)
	v_mfma_f32_16x16x32_bf16 v[48:51], v[56:59], v[84:87], v[48:51]
	ds_read2_b64 v[56:59], v182 offset0:64 offset1:68
	v_pk_mul_f32 v[42:43], v[42:43], v[126:127] op_sel_hi:[1,0]
	v_pk_mul_f32 v[40:41], v[40:41], v[126:127] op_sel_hi:[1,0]
	s_waitcnt lgkmcnt(1)
	v_mfma_f32_16x16x32_bf16 v[44:47], v[144:147], v[84:87], v[44:47]
	ds_read2_b64 v[144:147], v183 offset0:96 offset1:100
	v_pk_mul_f32 v[38:39], v[38:39], v[126:127] op_sel_hi:[1,0]
	v_pk_mul_f32 v[36:37], v[36:37], v[126:127] op_sel_hi:[1,0]
	s_waitcnt lgkmcnt(1)
	v_mfma_f32_16x16x32_bf16 v[174:177], v[56:59], v[84:87], v[40:43]
	ds_read2_b64 v[178:181], v136 offset0:200 offset1:204
	s_nop 1
	ds_read2_b64 v[40:43], v131 offset0:136 offset1:140
	v_lshl_add_u64 v[148:149], v[100:101], 0, s[4:5]
	s_waitcnt lgkmcnt(2)
	v_mfma_f32_16x16x32_bf16 v[84:87], v[144:147], v[84:87], v[36:39]
	global_store_dwordx4 v[148:149], v[76:79], off
	ds_read2_b64 v[76:79], v137 offset0:8 offset1:12
	v_lshl_add_u64 v[144:145], v[102:103], 0, s[4:5]
	ds_read2_b64 v[36:39], v127 offset0:136 offset1:140
	s_waitcnt lgkmcnt(2)
	v_mfma_f32_16x16x32_bf16 v[32:35], v[40:43], v[80:83], v[32:35]
	ds_read2_b64 v[40:43], v130 offset0:168 offset1:172
	global_store_dwordx4 v[144:145], v[72:75], off
	global_store_dwordx4 v[148:149], v[64:67], off offset:2048
	global_store_dwordx4 v[148:149], v[68:71], off offset:3072
	v_lshl_add_u64 v[146:147], v[116:117], 0, s[4:5]
	s_waitcnt lgkmcnt(1)
	v_mfma_f32_16x16x32_bf16 v[56:59], v[36:39], v[80:83], v[60:63]
	v_mfma_f32_16x16x32_bf16 v[36:39], v[178:181], v[80:83], v[52:55]
	s_nop 2
	ds_read_b128 v[52:55], v167 offset:4352
	ds_read2_b64 v[64:67], v173 offset0:40 offset1:44
	ds_read2_b64 v[68:71], v182 offset0:72 offset1:76
	ds_read_b128 v[72:75], v168 offset:4352
	s_waitcnt lgkmcnt(4)
	v_mfma_f32_16x16x32_bf16 v[60:63], v[40:43], v[80:83], v[140:143]
	v_mfma_f32_16x16x32_bf16 v[40:43], v[76:79], v[80:83], v[48:51]
	s_nop 1
	v_lshl_add_u64 v[142:143], v[104:105], 0, s[4:5]
	v_add_co_u32_e32 v76, vcc, s8, v142
	s_waitcnt lgkmcnt(2)
	v_mfma_f32_16x16x32_bf16 v[48:51], v[64:67], v[80:83], v[44:47]
	v_addc_co_u32_e32 v77, vcc, 0, v143, vcc
	v_add_co_u32_e32 v64, vcc, s8, v146
	s_nop 0
	ds_read2_b64 v[44:47], v183 offset0:104 offset1:108
	v_addc_co_u32_e32 v65, vcc, 0, v147, vcc
	global_store_dwordx4 v[76:77], v[52:55], off
	s_waitcnt lgkmcnt(1)
	global_store_dwordx4 v[64:65], v[72:75], off
	s_waitcnt lgkmcnt(0)
	v_mfma_f32_16x16x32_bf16 v[44:47], v[44:47], v[80:83], v[84:87]
	s_waitcnt lgkmcnt(0)
	s_barrier
	v_mfma_f32_16x16x32_bf16 v[52:55], v[68:71], v[80:83], v[174:177]
	s_cbranch_scc1 .LBB0_732
	s_cmp_gt_u32 s14, 28
	s_waitcnt vmcnt(6)
	v_mov_b64_e32 v[64:65], v[98:99]
	v_mov_b64_e32 v[66:67], v[96:97]
	v_mov_b64_e32 v[68:69], v[94:95]
	v_mov_b64_e32 v[70:71], v[92:93]
	ds_write_b128 v150, v[16:19]
	ds_write_b128 v151, v[20:23]
	ds_write_b128 v152, v[24:27] offset:17408
	ds_write_b128 v153, v[28:31] offset:17408
	s_cbranch_scc1 .LBB0_725
	v_lshl_add_u64 v[16:17], v[114:115], 0, s[4:5]
	v_add_co_u32_e32 v16, vcc, 0x3010000, v16
	v_lshl_add_u64 v[20:21], v[112:113], 0, s[4:5]
	s_nop 0
	v_addc_co_u32_e32 v17, vcc, 0, v17, vcc
	v_add_co_u32_e32 v20, vcc, 0x3010000, v20
	v_lshl_add_u64 v[24:25], v[110:111], 0, s[4:5]
	s_nop 0
	v_addc_co_u32_e32 v21, vcc, 0, v21, vcc
	v_add_co_u32_e32 v24, vcc, 0x117c0000, v24
	v_lshl_add_u64 v[28:29], v[108:109], 0, s[4:5]
	s_nop 0
	v_addc_co_u32_e32 v25, vcc, 0, v25, vcc
	v_add_co_u32_e32 v28, vcc, 0x117c0000, v28
	v_lshl_add_u64 v[64:65], v[106:107], 0, s[4:5]
	s_nop 0
	v_addc_co_u32_e32 v29, vcc, 0, v29, vcc
	v_add_co_u32_e32 v64, vcc, 0x2010000, v64
	global_load_dwordx4 v[16:19], v[16:17], off
	s_nop 0
	v_addc_co_u32_e32 v65, vcc, 0, v65, vcc
	global_load_dwordx4 v[20:23], v[20:21], off
	s_nop 0
	global_load_dwordx4 v[24:27], v[24:25], off
	s_nop 0
	global_load_dwordx4 v[28:31], v[28:29], off
	s_nop 0
	global_load_dwordx2 v[70:71], v[64:65], off
	global_load_dwordx2 v[68:69], v[64:65], off offset:32
	global_load_dwordx2 v[66:67], v[64:65], off offset:64
	s_nop 0
	global_load_dwordx2 v[64:65], v[64:65], off offset:96
	s_branch .LBB0_725
